# conv phase: rotate the starting wave per small weight matrix (out/attn+rwkv/lora/cmp/bias) so no wave gets more than ~5 transpose items instead of 14
# speedup vs baseline: 1.0072x; 1.0072x over previous
; #define LAS __attribute__((address_space(3)))
; DI void conv_mat(const float* W, int K, int N, int NP, bf16_t* WT, LAS float* scr, int gw, int NGW, int lane) {
;     const int nblk = NP / 32, nit = (K / 64) * nblk;
;     for (int it = gw; it < nit; it += NGW) tr_item(W, K, N, WT, scr, it, lane, nblk);
; DI void phase_conv(const Args& a, int l, LAS unsigned char* lds) {
;     ...
;     const int gw = blockIdx.x * 8 + wid, NGW = gridDim.x * 8;
;     bf16_t* W = (bf16_t*)(a.ws + WS_W);
;     conv_mat(a.in[I_WIN] + (size_t)l * 1024 * NPROJ, 1024, NPROJ, NPROJ_P, W + W_IN, scr, gw, NGW, lane);
;     conv_mat(a.in[I_WUP] + (size_t)l * 1024 * 4096, 1024, 4096, 4096, W + W_UP, scr, gw, NGW, lane);
;     conv_mat(a.in[I_WDOWN] + (size_t)l * 1024 * 4096, 4096, 1024, 1024, W + W_DOWN, scr, gw, NGW, lane);
;     conv_mat(a.in[I_WOUT] + (size_t)l * 1024 * 1024, 1024, 1024, 1024, W + W_OUT, scr, gw, NGW, lane);
.LBB0_1048:
	s_or_b64 exec, exec, s[2:3]
	v_readlane_b32 s2, v248, 54
	s_add_i32 s2, s2, 1408
	s_and_b32 s2, s2, 0x7ff
	v_add_u32_e32 v0, s2, v15
	s_lshl_b32 s2, s2, 5
	v_writelane_b32 v247, s2, 42
	s_movk_i32 s2, 0x200
	v_cmp_gt_i32_e32 vcc, s2, v0
	s_and_saveexec_b64 s[2:3], vcc
	s_cbranch_execz .LBB0_1115
	v_readlane_b32 s4, v246, 33
	v_readlane_b32 s5, v246, 34
	v_lshlrev_b32_e32 v2, 3, v14
	v_and_b32_e32 v2, 56, v2
	v_readlane_b32 s4, v245, 30
	v_readlane_b32 s14, v246, 43
	v_and_b32_e32 v4, 31, v1
	v_lshrrev_b32_e32 v10, 5, v14
	v_lshrrev_b32_e32 v7, 3, v14
	v_lshlrev_b32_e32 v128, 1, v2
	v_readlane_b32 s5, v245, 31
	v_readlane_b32 s8, v246, 37
	v_readlane_b32 s15, v246, 44
	s_add_u32 s0, s14, s0
	v_lshl_add_u32 v5, v4, 2, v12
	v_mul_u32_u24_e32 v6, 0x84, v10
	v_mul_u32_u24_e32 v8, 0x84, v2
	v_lshl_add_u64 v[2:3], s[4:5], 0, v[128:129]
	v_lshlrev_b32_e32 v9, 2, v7
	v_readlane_b32 s4, v247, 42
	s_addc_u32 s1, s15, s1
	v_add3_u32 v11, v12, v8, v9
	v_lshlrev_b32_e32 v19, 5, v15
	v_add_u32_e32 v20, s4, v7
	s_lshl_b32 s8, s76, 5
	v_add_u32_e32 v21, s4, v4
	s_mov_b64 s[4:5], 0
	v_add_u32_e32 v22, v5, v6
	v_mov_b32_e32 v23, v0
	v_readlane_b32 s6, v246, 35
	v_readlane_b32 s7, v246, 36
	v_readlane_b32 s9, v246, 38
	v_readlane_b32 s10, v246, 39
	v_readlane_b32 s11, v246, 40
	v_readlane_b32 s12, v246, 41
	v_readlane_b32 s13, v246, 42
	v_readlane_b32 s16, v246, 45
	v_readlane_b32 s17, v246, 46
	v_readlane_b32 s18, v246, 47
	v_readlane_b32 s19, v246, 48
	s_branch .LBB0_1051

; #define LAS __attribute__((address_space(3)))
; DI void conv_mat(const float* W, int K, int N, int NP, bf16_t* WT, LAS float* scr, int gw, int NGW, int lane) {
;     const int nblk = NP / 32, nit = (K / 64) * nblk;
;     for (int it = gw; it < nit; it += NGW) tr_item(W, K, N, WT, scr, it, lane, nblk);
; DI void phase_conv(const Args& a, int l, LAS unsigned char* lds) {
;     ...
;     conv_mat(a.in[I_WATTN] + (size_t)l * 512 * 1024, 512, 1024, 1024, W + W_A, scr, gw, NGW, lane);
;     conv_mat(a.in[I_WRWKV] + (size_t)l * 512 * 1024, 512, 1024, 1024, W + W_B, scr, gw, NGW, lane);
.LBB0_1115:
	s_or_b64 exec, exec, s[2:3]
	v_readlane_b32 s0, v248, 54
	s_add_i32 s0, s0, 896
	s_and_b32 s0, s0, 0x7ff
	v_add_u32_e32 v0, s0, v15
	s_lshl_b32 s0, s0, 5
	v_writelane_b32 v247, s0, 42
	s_movk_i32 s0, 0x100
	v_cmp_gt_i32_e32 vcc, s0, v0
	s_and_saveexec_b64 s[0:1], vcc
	s_cbranch_execz .LBB0_1248
	v_lshlrev_b32_e32 v2, 3, v14
	v_readlane_b32 s4, v245, 10
	v_and_b32_e32 v2, 56, v2
	v_readlane_b32 s6, v245, 32
	v_readlane_b32 s5, v245, 11
	v_lshlrev_b32_e32 v128, 1, v2
	v_readlane_b32 s7, v245, 33
	s_lshl_b64 s[2:3], s[4:5], 19
	s_lshl_b64 s[4:5], s[4:5], 21
	v_readlane_b32 s8, v246, 17
	v_and_b32_e32 v3, 31, v1
	v_lshrrev_b32_e32 v19, 5, v14
	v_lshrrev_b32_e32 v8, 3, v14
	v_lshl_add_u64 v[4:5], s[6:7], 0, v[128:129]
	v_readlane_b32 s6, v247, 42
	v_readlane_b32 s9, v246, 18
	v_readlane_b32 s10, v246, 19
	s_add_u32 s4, s8, s4
	v_lshl_add_u32 v6, v3, 2, v12
	v_mul_u32_u24_e32 v7, 0x84, v19
	v_mul_u32_u24_e32 v9, 0x84, v2
	v_lshlrev_b32_e32 v10, 2, v8
	v_add_u32_e32 v22, s6, v8
	v_add_u32_e32 v23, s6, v3
	s_addc_u32 s5, s9, s5
	v_add3_u32 v20, v12, v9, v10
	v_lshlrev_b32_e32 v21, 5, v15
	s_lshl_b32 s10, s76, 5
	s_mov_b64 s[6:7], 0
	v_add_u32_e32 v24, v6, v7
	v_mov_b32_e32 v3, v23
	v_mov_b32_e32 v30, v22
	v_mov_b32_e32 v31, v0
	v_readlane_b32 s11, v246, 20
	v_readlane_b32 s12, v246, 21
	v_readlane_b32 s13, v246, 22
	v_readlane_b32 s14, v246, 23
	v_readlane_b32 s15, v246, 24
	v_readlane_b32 s16, v246, 25
	v_readlane_b32 s17, v246, 26
	v_readlane_b32 s18, v246, 27
	v_readlane_b32 s19, v246, 28
	v_readlane_b32 s20, v246, 29
	v_readlane_b32 s21, v246, 30
	v_readlane_b32 s22, v246, 31
	v_readlane_b32 s23, v246, 32
	s_branch .LBB0_1118

; #define LAS __attribute__((address_space(3)))
; DI void conv_mat(const float* W, int K, int N, int NP, bf16_t* WT, LAS float* scr, int gw, int NGW, int lane) {
;     const int nblk = NP / 32, nit = (K / 64) * nblk;
;     for (int it = gw; it < nit; it += NGW) tr_item(W, K, N, WT, scr, it, lane, nblk);
; DI void phase_conv(const Args& a, int l, LAS unsigned char* lds) {
;     ...
;     conv_mat(a.in[I_WLORA] + (size_t)l * 64 * 512, 64, 512, 512, W + W_WL, scr, gw, NGW, lane);
;     conv_mat(a.in[I_ALORA] + (size_t)l * 64 * 512, 64, 512, 512, W + W_AL, scr, gw, NGW, lane);
.LBB0_1248:
	s_or_b64 exec, exec, s[0:1]
	v_readlane_b32 s0, v248, 54
	s_add_i32 s0, s0, 480
	s_and_b32 s0, s0, 0x7ff
	v_add_u32_e32 v0, s0, v15
	s_lshl_b32 s0, s0, 5
	v_writelane_b32 v247, s0, 42
	v_cmp_lt_i32_e32 vcc, 15, v0
	s_and_saveexec_b64 s[0:1], vcc
	s_xor_b64 s[0:1], exec, s[0:1]
	v_and_b32_e32 v16, 31, v1
	v_lshrrev_b32_e32 v17, 5, v14
	s_andn2_saveexec_b64 s[0:1], s[0:1]
	s_cbranch_execz .LBB0_1384
	v_lshlrev_b32_e32 v2, 3, v14
	v_readlane_b32 s4, v245, 10
	v_and_b32_e32 v2, 56, v2
	v_readlane_b32 s6, v245, 48
	v_readlane_b32 s5, v245, 11
	v_readlane_b32 s8, v246, 17
	v_lshlrev_b32_e32 v128, 1, v2
	v_readlane_b32 s7, v245, 49
	s_lshl_b64 s[2:3], s[4:5], 15
	s_lshl_b64 s[4:5], s[4:5], 17
	v_readlane_b32 s14, v246, 23
	v_lshrrev_b32_e32 v7, 3, v14
	v_lshl_add_u64 v[4:5], s[6:7], 0, v[128:129]
	v_readlane_b32 s6, v247, 42
	v_readlane_b32 s10, v246, 19
	v_readlane_b32 s15, v246, 24
	s_add_u32 s4, s14, s4
	v_lshl_add_u32 v3, v16, 2, v12
	v_mul_u32_u24_e32 v6, 0x84, v17
	v_mul_u32_u24_e32 v8, 0x84, v2
	v_lshlrev_b32_e32 v9, 2, v7
	v_add_u32_e32 v21, s6, v7
	v_add_u32_e32 v22, s6, v16
	s_addc_u32 s5, s15, s5
	v_add3_u32 v19, v12, v8, v9
	v_lshlrev_b32_e32 v20, 5, v15
	s_lshl_b32 s10, s76, 5
	s_mov_b64 s[6:7], 0
	v_add_u32_e32 v23, v3, v6
	v_mov_b32_e32 v3, v22
	v_mov_b32_e32 v29, v21
	v_mov_b32_e32 v30, v0
	v_readlane_b32 s9, v246, 18
	v_readlane_b32 s11, v246, 20
	v_readlane_b32 s12, v246, 21
	v_readlane_b32 s13, v246, 22
	v_readlane_b32 s16, v246, 25
	v_readlane_b32 s17, v246, 26
	v_readlane_b32 s18, v246, 27
	v_readlane_b32 s19, v246, 28
	v_readlane_b32 s20, v246, 29
	v_readlane_b32 s21, v246, 30
	v_readlane_b32 s22, v246, 31
	v_readlane_b32 s23, v246, 32
	s_branch .LBB0_1253

; #define LAS __attribute__((address_space(3)))
; DI void conv_mat(const float* W, int K, int N, int NP, bf16_t* WT, LAS float* scr, int gw, int NGW, int lane) {
;     const int nblk = NP / 32, nit = (K / 64) * nblk;
;     for (int it = gw; it < nit; it += NGW) tr_item(W, K, N, WT, scr, it, lane, nblk);
; DI void phase_conv(const Args& a, int l, LAS unsigned char* lds) {
;     ...
;     conv_mat(a.in[I_GLORA] + (size_t)l * 128 * 512, 128, 512, 512, W + W_GL, scr, gw, NGW, lane);
.LBB0_1384:
	s_or_b64 exec, exec, s[0:1]
	v_readlane_b32 s0, v248, 54
	s_add_i32 s0, s0, 512
	s_and_b32 s0, s0, 0x7ff
	v_add_u32_e32 v0, s0, v15
	s_lshl_b32 s0, s0, 5
	v_writelane_b32 v247, s0, 42
	v_cmp_lt_i32_e32 vcc, 31, v0
	v_mul_i32_i24_e32 v19, 0x84, v17
	s_and_saveexec_b64 s[0:1], vcc
	s_xor_b64 s[0:1], exec, s[0:1]
	v_lshlrev_b32_e32 v2, 3, v14
	v_lshrrev_b32_e32 v18, 3, v14
	v_and_b32_e32 v128, 56, v2
	v_mul_i32_i24_e32 v19, 0x84, v17
	v_mul_u32_u24_e32 v10, 0x84, v128
	v_or_b32_e32 v20, 8, v18
	v_or_b32_e32 v21, 16, v18
	v_or_b32_e32 v22, 24, v18
	v_lshlrev_b32_e32 v13, 5, v15
	s_or_saveexec_b64 s[0:1], s[0:1]
	v_lshl_add_u32 v23, v16, 2, v12
	s_xor_b64 exec, exec, s[0:1]
	s_cbranch_execz .LBB0_1454
	v_readlane_b32 s4, v246, 17
	v_readlane_b32 s2, v245, 10
	v_readlane_b32 s5, v246, 18
	v_lshlrev_b32_e32 v2, 3, v14
	v_readlane_b32 s3, v245, 11
	v_and_b32_e32 v128, 56, v2
	v_readlane_b32 s4, v245, 40
	s_lshl_b64 s[2:3], s[2:3], 18
	v_readlane_b32 s16, v246, 29
	v_lshlrev_b32_e32 v2, 1, v128
	v_mov_b32_e32 v3, v129
	v_readlane_b32 s5, v245, 41
	v_readlane_b32 s8, v246, 21
	v_readlane_b32 s17, v246, 30
	s_add_u32 s2, s16, s2
	v_mul_u32_u24_e32 v10, 0x84, v128
	v_lshl_add_u64 v[2:3], s[4:5], 0, v[2:3]
	v_lshlrev_b32_e32 v4, 2, v18
	v_readlane_b32 s4, v247, 42
	s_addc_u32 s3, s17, s3
	v_add3_u32 v11, v12, v10, v4
	v_or_b32_e32 v20, 8, v18
	v_or_b32_e32 v21, 16, v18
	v_or_b32_e32 v22, 24, v18
	v_add_u32_e32 v24, s4, v18
	s_lshl_b32 s8, s76, 5
	v_add_u32_e32 v25, s4, v16
	s_mov_b64 s[4:5], 0
	v_add_u32_e32 v26, v23, v19
	v_mov_b32_e32 v27, v0
	v_readlane_b32 s6, v246, 19
	v_readlane_b32 s7, v246, 20
	v_readlane_b32 s9, v246, 22
	v_readlane_b32 s10, v246, 23
	v_readlane_b32 s11, v246, 24
	v_readlane_b32 s12, v246, 25
	v_readlane_b32 s13, v246, 26
	v_readlane_b32 s14, v246, 27
	v_readlane_b32 s15, v246, 28
	v_readlane_b32 s18, v246, 31
	v_readlane_b32 s19, v246, 32
	s_branch .LBB0_1389

; DI void phase_conv(const Args& a, int l, LAS unsigned char* lds) {
;     ...
;     for (int kv = 0; kv < 2; ++kv) {
;         conv_mat(a.in[I_CMPW1] + (size_t)(l * 2 + kv) * 2048 * 128, 2048, 128, 128, W + W_C1 + kv * 262144, scr, gw, NGW, lane);
;         conv_mat(a.in[I_CMPW2] + (size_t)(l * 2 + kv) * 128 * 64, 128, 64, 64, W + W_C2 + kv * 8192, scr, gw, NGW, lane);
;     }
.LBB0_1454:
	s_or_b64 exec, exec, s[0:1]
	v_readlane_b32 s0, v248, 54
	s_add_i32 s0, s0, 640
	s_and_b32 s0, s0, 0x7ff
	v_add_u32_e32 v0, s0, v15
	s_lshl_b32 s0, s0, 5
	v_writelane_b32 v247, s0, 42
	v_readlane_b32 s0, v245, 10
	v_readlane_b32 s1, v245, 11
	s_lshl_b32 s12, s0, 1
	v_readlane_b32 s0, v245, 14
	v_lshlrev_b64 v[4:5], 1, v[128:129]
	v_readlane_b32 s1, v245, 15
	v_add_u32_e32 v6, v12, v10
	v_cmp_gt_i32_e64 s[38:39], s33, v0
	v_lshl_add_u64 v[2:3], s[0:1], 0, v[4:5]
	s_mov_b64 s[0:1], 0x22c0000
	v_lshl_add_u64 v[2:3], v[2:3], 0, s[0:1]
	v_readlane_b32 s0, v245, 52
	v_readlane_b32 s1, v245, 53
	v_lshl_add_u32 v24, v18, 2, v6
	v_lshl_add_u32 v25, v20, 2, v6
	v_lshl_add_u64 v[4:5], s[0:1], 0, v[4:5]
	v_readlane_b32 s0, v247, 42
	v_lshl_add_u32 v26, v21, 2, v6
	v_lshl_add_u32 v27, v22, 2, v6
	v_cmp_gt_i32_e64 s[40:41], 4, v0
	v_add_u32_e32 v28, s0, v13
	s_mov_b32 s13, 0
	s_mov_b64 s[0:1], -1
	s_branch .LBB0_1456

; DI void phase_conv(const Args& a, int l, LAS unsigned char* lds) {
;     ...
;     for (int u = gw; u < 64; u += NGW) {
;         const int kv = u >> 5, ng = (u >> 4) & 1, kp = u & 15, n = ng * 64 + lane;
;         const float* pos = a.in[I_CMPPOS] + (size_t)(l * 2 + kv) * 2048; const float* w1 = a.in[I_CMPW1] + (size_t)(l * 2 + kv) * 2048 * 128;
;         float acc8[8] = {0.f, 0.f, 0.f, 0.f, 0.f, 0.f, 0.f, 0.f};
.LBB0_1590:
	v_readlane_b32 s0, v248, 54
	s_add_i32 s0, s0, 464
	s_and_b32 s0, s0, 0x7ff
	v_add_u32_e32 v0, s0, v15
	s_lshl_b32 s1, s0, 7
	v_writelane_b32 v247, s1, 45
	s_lshl_b32 s1, s0, 2
	v_writelane_b32 v248, s1, 20
	s_lshl_b32 s1, s0, 5
	v_writelane_b32 v247, s1, 42
	v_cmp_gt_i32_e32 vcc, 64, v0
	s_and_saveexec_b64 s[0:1], vcc
	s_cbranch_execz .LBB0_1595
	v_readlane_b32 s2, v247, 45
	v_mov_b32_e32 v17, v0
	s_nop 0
	v_lshl_add_u32 v16, v15, 7, s2
	v_readlane_b32 s2, v248, 20
	s_nop 1
	v_lshl_add_u32 v15, v15, 2, s2
	s_mov_b64 s[2:3], 0

; DI void phase_conv(const Args& a, int l, LAS unsigned char* lds) {
;     ...
;     if (l == 0) {
;         float* ssz = (float*)(a.ws + WS_SS);
;         for (int i = blockIdx.x * 512 + tid; i < 3 * M_TOK; i += gridDim.x * 512) ssz[i] = 0.f;
;         bf16_t* U = (bf16_t*)(a.ws + WS_U);
;         for (int m = gw; m < M_TOK; m += NGW) rms_row(a.in[I_X] + (size_t)m * DM, a.in[I_MIXNORM], U + (size_t)m * DM, lane);
.LBB0_1595:
	s_or_b64 exec, exec, s[0:1]
	v_readlane_b32 s0, v248, 54
	v_lshrrev_b32_e32 v0, 6, v155
	v_add_u32_e32 v0, s0, v0
	s_lshl_b32 s1, s0, 5
	v_writelane_b32 v247, s1, 42
	s_lshl_b32 s1, s0, 7
	v_writelane_b32 v247, s1, 45
	s_lshl_b32 s1, s0, 2
	v_writelane_b32 v248, s1, 20
	v_readlane_b32 s0, v245, 24
	v_readlane_b32 s1, v245, 25
	v_readlane_b32 s6, v245, 22
	s_and_b64 vcc, exec, s[0:1]
	v_readlane_b32 s7, v245, 23
	s_cbranch_vccz .LBB0_1603
	v_readlane_b32 s0, v248, 55
	s_nop 1
	v_add_u32_e32 v2, s0, v1
	s_mov_b32 s0, 0x18000
	v_cmp_gt_i32_e32 vcc, s0, v2
	s_and_saveexec_b64 s[0:1], vcc
	v_readlane_b32 s5, v248, 56
	s_cbranch_execz .LBB0_1599
	s_mov_b64 s[2:3], 0
